# v31 + gMLP LayerNorm phase: gamma/beta vectors hoisted out of the row loop (4 serialized load round-trips per row removed)
# speedup vs baseline: 1.0165x; 1.0021x over previous
; DI void phase_gmln(ArgsP AP) {
;     int tid = threadIdx.x; asm volatile("" : "+v"(tid)); const int lane = tid & 63, wave = tid >> 6;
;     const int gw = blockIdx.x * 8 + wave, NGW = gridDim.x * 8;
;     const bf16* UV = (const bf16*)(AP->ws + WS_BIG); bf16* VLN = (bf16*)(AP->ws + WS_BIG + 2 * U1);
;     const float* g = AP->in[14]; const float* bb = AP->in[15]; float* ogm = AP->out + O_GMV;
;     for (int r = gw; r < RT; r += NGW) {
;     ...
;         for (int j = 0; j < 4; ++j) { const int c = lane * 4 + 256 * j; const f32x4 o = v[j] * rstd * *(const f32x4*)(g + c) + *(const f32x4*)(bb + c);
.LBB0_236:
	s_andn2_b64 vcc, exec, s[0:1]
	s_cbranch_vccnz .LBB0_249
	v_mov_b32_e32 v0, v164
	v_readlane_b32 s0, v253, 3
	v_ashrrev_i32_e32 v1, 6, v0
	s_nop 0
	v_add_u32_e32 v4, s0, v1
	s_mov_b32 s0, 0x8080
	v_cmp_gt_i32_e32 vcc, s0, v4
	s_and_saveexec_b64 s[0:1], vcc
	s_cbranch_execz .LBB0_248
	s_load_dwordx2 s[2:3], s[86:87], 0x100
	s_load_dwordx4 s[20:23], s[86:87], 0x70
	v_lshlrev_b32_e32 v1, 2, v0
	v_and_b32_e32 v0, 63, v0
	v_ashrrev_i32_e32 v5, 31, v4
	v_and_b32_e32 v6, 0xfc, v1
	v_lshlrev_b32_e32 v12, 3, v0
	v_lshlrev_b64 v[0:1], 11, v[4:5]
	v_lshlrev_b32_e32 v2, 2, v6
	s_waitcnt lgkmcnt(0)
	s_add_u32 s16, s2, 0x8080000
	v_mov_b32_e32 v3, v97
	v_lshl_add_u64 v[14:15], s[24:25], 0, v[0:1]
	v_lshlrev_b64 v[0:1], 12, v[4:5]
	s_addc_u32 s17, s3, 0
	v_lshl_add_u64 v[8:9], s[20:21], 0, v[2:3]
	v_lshl_add_u64 v[10:11], s[22:23], 0, v[2:3]
	v_mov_b32_e32 v13, v97
	v_lshl_add_u64 v[16:17], s[24:25], 0, v[0:1]
	global_load_dwordx4 v[56:59], v[8:9], off
	global_load_dwordx4 v[60:63], v[8:9], off offset:1024
	global_load_dwordx4 v[64:67], v[8:9], off offset:2048
	global_load_dwordx4 v[68:71], v[8:9], off offset:3072
	global_load_dwordx4 v[72:75], v[10:11], off
	global_load_dwordx4 v[76:79], v[10:11], off offset:1024
	global_load_dwordx4 v[80:83], v[10:11], off offset:2048
	global_load_dwordx4 v[84:87], v[10:11], off offset:3072
	s_mov_b64 s[20:21], 0
	s_branch .LBB0_240

; DI unsigned pk2(float lo, float hi) { f32x2 v = {lo, hi}; bf16x2_t b = __builtin_convertvector(v, bf16x2_t); return __builtin_bit_cast(unsigned, b); }
; DI float bflo(unsigned u) { return __uint_as_float(u << 16); }
; DI float bfhi(unsigned u) { return __uint_as_float(u & 0xffff0000u); }
; DI void phase_gmln(ArgsP AP) {
;     ...
;         f32x4 v[4]; float s = 0.f;
; #pragma unroll
;         for (int j = 0; j < 4; ++j) { const u32x2 w = *(const u32x2*)(UV + (size_t)r * 2048 + 1024 + lane * 4 + 256 * j); v[j] = (f32x4){bflo(w.x), bfhi(w.x), bflo(w.y), bfhi(w.y)}; s += (v[j][0] + v[j][1]) + (v[j][2] + v[j][3]); }
;         const float mean = wave_sum(s) * (1.f / DM); float s2 = 0.f;
; #pragma unroll
;         for (int j = 0; j < 4; ++j) { v[j] = v[j] - mean; s2 += v[j][0] * v[j][0] + v[j][1] * v[j][1] + v[j][2] * v[j][2] + v[j][3] * v[j][3]; }
;         const float rstd = 1.f / sqrtf(wave_sum(s2) * (1.f / DM) + EPS);
; #pragma unroll
;         for (int j = 0; j < 4; ++j) { const int c = lane * 4 + 256 * j; const f32x4 o = v[j] * rstd * *(const f32x4*)(g + c) + *(const f32x4*)(bb + c);
;             u32x2 w; w.x = pk2(o[0], o[1]); w.y = pk2(o[2], o[3]); *(u32x2*)(VLN + (size_t)r * DM + c) = w;
;             if (r >= RP) *(f32x4*)(ogm + (size_t)(r - RP) * DM + c) = o; }
.LBB0_240:
	v_lshl_add_u64 v[0:1], v[16:17], 0, v[12:13]
	v_add_co_u32_e32 v0, vcc, 0xaa00000, v0
	s_movk_i32 s2, 0x7fff
	s_nop 0
	v_addc_co_u32_e32 v1, vcc, 0, v1, vcc
	global_load_dwordx2 v[18:19], v[0:1], off offset:2048
	global_load_dwordx2 v[20:21], v[0:1], off offset:2560
	global_load_dwordx2 v[22:23], v[0:1], off offset:3072
	global_load_dwordx2 v[26:27], v[0:1], off offset:3584
	v_cmp_lt_i32_e64 s[40:41], s2, v4
	v_add_u32_e32 v96, 0xffff8000, v4
	v_lshlrev_b64 v[34:35], 12, v[96:97]
	v_lshlrev_b32_e32 v96, 2, v6
	s_waitcnt vmcnt(3)
	v_lshlrev_b32_e32 v45, 16, v19
	v_lshlrev_b32_e32 v44, 16, v18
	v_and_b32_e32 v47, 0xffff0000, v19
	v_and_b32_e32 v46, 0xffff0000, v18
	s_waitcnt vmcnt(2)
	v_lshlrev_b32_e32 v39, 16, v21
	v_lshlrev_b32_e32 v38, 16, v20
	v_and_b32_e32 v37, 0xffff0000, v21
	v_and_b32_e32 v36, 0xffff0000, v20
	s_waitcnt vmcnt(1)
	v_lshlrev_b32_e32 v31, 16, v23
	v_and_b32_e32 v29, 0xffff0000, v23
	s_waitcnt vmcnt(0)
	v_lshlrev_b32_e32 v25, 16, v26
	v_and_b32_e32 v20, 0xffff0000, v26
	v_lshlrev_b32_e32 v23, 16, v27
	v_and_b32_e32 v19, 0xffff0000, v27
	v_pk_add_f32 v[26:27], v[44:45], v[46:47]
	v_pk_add_f32 v[48:49], v[38:39], v[36:37]
	v_lshlrev_b32_e32 v33, 16, v22
	v_and_b32_e32 v21, 0xffff0000, v22
	v_add_f32_e32 v5, v26, v27
	v_pk_add_f32 v[26:27], v[48:49], v[48:49] op_sel:[0,1] op_sel_hi:[1,0]
	v_add_f32_e32 v22, v33, v21
	v_add_f32_e32 v18, v31, v29
	v_add_f32_e32 v24, 0, v5
	v_mov_b32_e32 v27, v20
	v_pk_add_f32 v[48:49], v[22:23], v[18:19]
	v_pk_add_f32 v[26:27], v[24:25], v[26:27]
	s_nop 0
	v_pk_add_f32 v[26:27], v[26:27], v[48:49]
	s_nop 0
	v_add_f32_e32 v5, v26, v27
	s_nop 1
	v_add_f32_dpp v5, v5, v5 quad_perm:[1,0,3,2] row_mask:0xf bank_mask:0xf bound_ctrl:1
	s_nop 1
	v_add_f32_dpp v5, v5, v5 quad_perm:[2,3,0,1] row_mask:0xf bank_mask:0xf bound_ctrl:1
	s_nop 1
	v_add_f32_dpp v5, v5, v5 row_ror:4 row_mask:0xf bank_mask:0xf bound_ctrl:1
	s_nop 1
	v_add_f32_dpp v5, v5, v5 row_ror:8 row_mask:0xf bank_mask:0xf bound_ctrl:1
	s_nop 0
	v_readlane_b32 s6, v5, 16
	v_readlane_b32 s7, v5, 48
	v_readlane_b32 s2, v5, 0
	v_readlane_b32 s3, v5, 32
	v_mov_b32_e32 v26, s6
	v_mov_b32_e32 v27, s7
	v_pk_add_f32 v[26:27], s[2:3], v[26:27]
	s_nop 0
	v_add_f32_e32 v5, v26, v27
	v_fmac_f32_e32 v46, 0xba800000, v5
	v_fmac_f32_e32 v36, 0xba800000, v5
	v_fmac_f32_e32 v44, 0xba800000, v5
	v_fmac_f32_e32 v38, 0xba800000, v5
	v_mov_b32_e32 v48, v46
	v_mov_b32_e32 v49, v36
	v_fmac_f32_e32 v45, 0xba800000, v5
	v_fmac_f32_e32 v39, 0xba800000, v5
	v_fmac_f32_e32 v21, 0xba800000, v5
	v_fmac_f32_e32 v20, 0xba800000, v5
	v_fmac_f32_e32 v25, 0xba800000, v5
	v_mov_b32_e32 v26, v44
	v_mov_b32_e32 v27, v38
	v_pk_mul_f32 v[48:49], v[48:49], v[48:49]
	v_fmac_f32_e32 v47, 0xba800000, v5
	v_fmac_f32_e32 v37, 0xba800000, v5
	v_fmac_f32_e32 v33, 0xba800000, v5
	v_fmac_f32_e32 v23, 0xba800000, v5
	v_mov_b32_e32 v50, v45
	v_mov_b32_e32 v51, v39
	v_mov_b32_e32 v32, v25
	v_pk_mul_f32 v[54:55], v[20:21], v[20:21]
	v_pk_fma_f32 v[26:27], v[26:27], v[26:27], v[48:49]
	v_fmac_f32_e32 v31, 0xba800000, v5
	v_fmac_f32_e32 v19, 0xba800000, v5
	v_mov_b32_e32 v52, v47
	v_mov_b32_e32 v53, v37
	v_mov_b32_e32 v30, v23
	v_pk_fma_f32 v[54:55], v[32:33], v[32:33], v[54:55]
	v_pk_fma_f32 v[26:27], v[50:51], v[50:51], v[26:27]
	v_fmac_f32_e32 v29, 0xba800000, v5
	v_mov_b32_e32 v28, v19
	v_pk_fma_f32 v[48:49], v[30:31], v[30:31], v[54:55]
	v_pk_fma_f32 v[26:27], v[52:53], v[52:53], v[26:27]
	v_pk_fma_f32 v[48:49], v[28:29], v[28:29], v[48:49]
	v_add_f32_e32 v5, v26, v27
	v_add_f32_e32 v5, v49, v5
	v_add_f32_e32 v5, v48, v5
	v_mov_b32_e32 v48, v44
	v_mov_b32_e32 v49, v46
	v_add_f32_dpp v5, v5, v5 quad_perm:[1,0,3,2] row_mask:0xf bank_mask:0xf bound_ctrl:1
	v_mov_b32_e32 v46, v45
	s_nop 0
	v_add_f32_dpp v5, v5, v5 quad_perm:[2,3,0,1] row_mask:0xf bank_mask:0xf bound_ctrl:1
	s_nop 1
	v_add_f32_dpp v5, v5, v5 row_ror:4 row_mask:0xf bank_mask:0xf bound_ctrl:1
	s_nop 1
	v_add_f32_dpp v5, v5, v5 row_ror:8 row_mask:0xf bank_mask:0xf bound_ctrl:1
	s_nop 0
	v_readlane_b32 s6, v5, 16
	v_readlane_b32 s7, v5, 48
	v_readlane_b32 s2, v5, 0
	v_readlane_b32 s3, v5, 32
	v_mov_b32_e32 v26, s6
	v_mov_b32_e32 v27, s7
	v_pk_add_f32 v[26:27], s[2:3], v[26:27]
	s_nop 0
	v_add_f32_e32 v5, v26, v27
	v_fmamk_f32 v5, v5, 0x3a800000, v221
	v_mul_f32_e32 v7, 0x4f800000, v5
	v_cmp_gt_f32_e32 vcc, s13, v5
	v_lshl_add_u64 v[26:27], s[16:17], 0, v[34:35]
	s_nop 0
	v_cndmask_b32_e32 v5, v5, v7, vcc
	v_sqrt_f32_e32 v7, v5
	s_nop 0
	v_add_u32_e32 v18, -1, v7
	v_add_u32_e32 v22, 1, v7
	v_fma_f32 v24, -v18, v7, v5
	v_fma_f32 v28, -v22, v7, v5
	v_cmp_ge_f32_e64 s[42:43], 0, v24
	s_nop 1
	v_cndmask_b32_e64 v7, v7, v18, s[42:43]
	v_cmp_lt_f32_e64 s[42:43], 0, v28
	s_nop 1
	v_cndmask_b32_e64 v7, v7, v22, s[42:43]
	v_mul_f32_e32 v18, 0x37800000, v7
	v_cndmask_b32_e32 v7, v7, v18, vcc
	v_cmp_class_f32_e32 vcc, v5, v222
	s_nop 1
	v_cndmask_b32_e32 v5, v7, v5, vcc
	v_div_scale_f32 v7, s[2:3], v5, v5, 1.0
	v_rcp_f32_e32 v18, v7
	v_div_scale_f32 v22, vcc, 1.0, v5, 1.0
	v_fma_f32 v24, -v7, v18, 1.0
	v_fmac_f32_e32 v18, v24, v18
	v_mul_f32_e32 v24, v22, v18
	v_fma_f32 v28, -v7, v24, v22
	v_fmac_f32_e32 v24, v28, v18
	v_fma_f32 v7, -v7, v24, v22
	v_div_fmas_f32 v7, v7, v18, v24
	v_div_fixup_f32 v34, v7, v5, 1.0
	v_pk_mul_f32 v[44:45], v[48:49], v[34:35] op_sel_hi:[1,0]
	v_pk_mul_f32 v[46:47], v[46:47], v[34:35] op_sel_hi:[1,0]
	v_pk_fma_f32 v[0:1], v[56:57], v[44:45], v[72:73]
	v_lshl_add_u64 v[40:41], v[14:15], 0, v[12:13]
	v_pk_fma_f32 v[2:3], v[58:59], v[46:47], v[74:75]
	v_add_co_u32_e32 v44, vcc, 0x12b00000, v40
	v_cvt_pk_bf16_f32 v42, v0, v1
	v_cvt_pk_bf16_f32 v43, v2, v3
	v_addc_co_u32_e32 v45, vcc, 0, v41, vcc
	global_store_dwordx2 v[44:45], v[42:43], off
	s_and_saveexec_b64 s[2:3], s[40:41]
	s_cbranch_execz .LBB0_242
	v_lshl_add_u64 v[42:43], v[26:27], 0, v[96:97]
	global_store_dwordx4 v[42:43], v[0:3], off
; DI unsigned pk2(float lo, float hi) { f32x2 v = {lo, hi}; bf16x2_t b = __builtin_convertvector(v, bf16x2_t); return __builtin_bit_cast(unsigned, b); }
; DI void phase_gmln(ArgsP AP) {
;     ...
;         for (int j = 0; j < 4; ++j) { const int c = lane * 4 + 256 * j; const f32x4 o = v[j] * rstd * *(const f32x4*)(g + c) + *(const f32x4*)(bb + c);
;             u32x2 w; w.x = pk2(o[0], o[1]); w.y = pk2(o[2], o[3]); *(u32x2*)(VLN + (size_t)r * DM + c) = w;
;             if (r >= RP) *(f32x4*)(ogm + (size_t)(r - RP) * DM + c) = o; }
.LBB0_242:
	s_or_b64 exec, exec, s[2:3]
	v_mov_b32_e32 v48, v38
	v_mov_b32_e32 v49, v36
	v_mov_b32_e32 v35, v34
	v_mov_b32_e32 v42, v34
	v_mov_b32_e32 v43, v34
	v_mov_b32_e32 v36, v39
	v_pk_mul_f32 v[36:37], v[36:37], v[42:43]
	v_pk_mul_f32 v[48:49], v[48:49], v[34:35]
	v_add_co_u32_e32 v38, vcc, 0x12b00000, v40
	v_pk_fma_f32 v[2:3], v[36:37], v[62:63], v[78:79]
	v_pk_fma_f32 v[0:1], v[48:49], v[60:61], v[76:77]
	v_cvt_pk_bf16_f32 v37, v2, v3
	v_cvt_pk_bf16_f32 v36, v0, v1
	v_addc_co_u32_e32 v39, vcc, 0, v41, vcc
	global_store_dwordx2 v[38:39], v[36:37], off offset:512
	s_and_saveexec_b64 s[2:3], s[40:41]
	s_cbranch_execz .LBB0_244
	v_lshl_add_u64 v[36:37], v[26:27], 0, v[96:97]
	global_store_dwordx4 v[36:37], v[0:3], off offset:1024
.LBB0_244:
	s_or_b64 exec, exec, s[2:3]
	v_mov_b32_e32 v32, v33
	v_mov_b32_e32 v33, v21
	v_mov_b32_e32 v28, v31
	v_pk_mul_f32 v[28:29], v[28:29], v[42:43]
	v_pk_mul_f32 v[32:33], v[32:33], v[34:35]
	v_add_co_u32_e32 v30, vcc, 0x12b00000, v40
	v_pk_fma_f32 v[2:3], v[28:29], v[66:67], v[82:83]
	v_pk_fma_f32 v[0:1], v[32:33], v[64:65], v[80:81]
	v_cvt_pk_bf16_f32 v29, v2, v3
	v_cvt_pk_bf16_f32 v28, v0, v1
	v_addc_co_u32_e32 v31, vcc, 0, v41, vcc
	global_store_dwordx2 v[30:31], v[28:29], off offset:1024
	s_and_saveexec_b64 s[2:3], s[40:41]
	s_cbranch_execz .LBB0_246
	v_lshl_add_u64 v[28:29], v[26:27], 0, v[96:97]
	global_store_dwordx4 v[28:29], v[0:3], off offset:2048
.LBB0_246:
	s_or_b64 exec, exec, s[2:3]
	v_mov_b32_e32 v24, v25
	v_mov_b32_e32 v25, v20
	v_mov_b32_e32 v20, v34
	v_mov_b32_e32 v21, v34
	v_mov_b32_e32 v18, v23
	v_pk_mul_f32 v[18:19], v[18:19], v[20:21]
	v_pk_mul_f32 v[20:21], v[24:25], v[34:35]
	v_add_co_u32_e32 v22, vcc, 0x12b00000, v40
	v_pk_fma_f32 v[2:3], v[18:19], v[70:71], v[86:87]
	v_pk_fma_f32 v[0:1], v[20:21], v[68:69], v[84:85]
	v_cvt_pk_bf16_f32 v19, v2, v3
	v_cvt_pk_bf16_f32 v18, v0, v1
	v_addc_co_u32_e32 v23, vcc, 0, v41, vcc
	global_store_dwordx2 v[22:23], v[18:19], off offset:1536
	s_and_saveexec_b64 s[2:3], s[40:41]
	s_cbranch_execz .LBB0_239
	v_lshl_add_u64 v[18:19], v[26:27], 0, v[96:97]
	global_store_dwordx4 v[18:19], v[0:3], off offset:3072
	s_branch .LBB0_239
